# convert_layer tile assignment rotated per job so every converting workgroup gets the same number of tiles (on top of the stack)
# speedup vs baseline: 1.0108x; 1.0060x over previous
; __device__ __forceinline__ void convert_job(unsigned char* smem, const float* src, int ld, int col0, int mapkind, int N, int K, const float* scale, bf16_t* dst, int vb, int vG) {
;     ...
;     const int w = tidx >> 6, lane = tidx & 63;
;     const int tn = N / 64, tk = K / 256, ntile = tn * tk;
;     for (int t = vb; t < ntile; t += vG) {
;         const int n0 = (t % tn) * 64, k0 = (t / tn) * 256;
;         const int np = n0 + lane; int sc;
;         if (mapkind == 0) sc = col0 + np;
; __device__ __forceinline__ void convert_layer(unsigned char* smem, const Params& P, int layer, int skip) {
;     ...
;     convert_job(smem, P.w_glu + (size_t)layer * 512 * 512, 512, 0, 0, 512, 512, nullptr, wb + W_GLU, vb, vG);
.LBB0_650:
	s_or_b64 exec, exec, s[24:25]
	v_readlane_b32 s4, v232, 43
	v_readlane_b32 s5, v232, 44
	s_mov_b32 s29, s75
	s_lshl_b64 s[40:41], s[28:29], 20
	v_readlane_b32 s100, v231, 40
	s_cmpk_eq_u32 s48, 0xf0
	s_cselect_b32 s101, 0x40, 0
	s_add_i32 s100, s100, s101
	s_sub_i32 s101, s100, s48
	s_cmp_ge_u32 s100, s48
	s_cselect_b32 s100, s101, s100
	s_cmpk_lt_u32 s100, 0x10
	s_cselect_b64 s[4:5], -1, 0
	s_mov_b32 s101, 0
	v_cndmask_b32_e64 v0, 0, 1, s[4:5]
	v_mov_b32_e32 v16, v186
	v_cmp_ne_u32_e64 s[24:25], 1, v0
	s_andn2_b64 vcc, exec, s[4:5]
	s_cbranch_vccnz .LBB0_653
	v_ashrrev_i32_e32 v0, 1, v16
	v_and_b32_e32 v13, 0xffffffe0, v0
	v_lshlrev_b32_e32 v0, 4, v16
	v_and_b32_e32 v0, 0x1f0, v0
	v_and_b32_e32 v12, 63, v16
	v_and_b32_e32 v18, 0xffffffc0, v16
	v_add_u32_e32 v21, 0, v0
	v_lshl_add_u64 v[10:11], s[36:37], 0, v[0:1]
	v_ashrrev_i32_e32 v0, 5, v16
	v_add_u32_e32 v14, 0x200, v16
	v_add_u32_e32 v15, 0x400, v16
	v_add_u32_e32 v16, 0x600, v16
	s_movk_i32 s6, 0x204
	s_mov_b64 s[4:5], 0xb80000
	v_ashrrev_i32_e32 v14, 5, v14
	v_ashrrev_i32_e32 v15, 5, v15
	v_ashrrev_i32_e32 v16, 5, v16
	s_add_u32 s2, s2, s40
	v_mad_u32_u24 v17, v12, s6, 0
	v_lshl_add_u64 v[10:11], v[10:11], 0, s[4:5]
	v_mul_lo_u32 v19, v0, s6
	v_mul_lo_u32 v20, v14, s6
	v_mul_lo_u32 v22, v15, s6
	v_mul_lo_u32 v23, v16, s6
	s_mov_b32 s4, s100
	s_addc_u32 s3, s3, s41
	s_lshl_b32 s29, s4, 6
	s_lshl_b32 s33, s48, 6
	v_add_u32_e32 v17, v17, v18
	v_add_u32_e32 v18, v21, v19
	v_add_u32_e32 v19, v21, v20
	v_add_u32_e32 v20, v21, v22
	v_add_u32_e32 v21, v21, v23
	s_mov_b32 s42, s4
	v_readlane_b32 s5, v231, 41

; __device__ __forceinline__ void convert_job(unsigned char* smem, const float* src, int ld, int col0, int mapkind, int N, int K, const float* scale, bf16_t* dst, int vb, int vG) {
;     ...
;     for (int t = vb; t < ntile; t += vG) {
;         const int n0 = (t % tn) * 64, k0 = (t / tn) * 256;
;         const int np = n0 + lane; int sc;
;         if (mapkind == 0) sc = col0 + np;
; __device__ __forceinline__ void convert_layer(unsigned char* smem, const Params& P, int layer, int skip) {
;     ...
;     for (int r = 0; r < 3; ++r) convert_job(smem, P.w_branch + ((size_t)layer * 3 + r) * 512 * 1024, 1024, 0, 0, 1024, 512, nullptr, wb + W_BR + (size_t)r * 1024 * 512, vb, vG);
.LBB0_653:
	s_mul_i32 s2, s28, 0x600000
	v_readlane_b32 s4, v232, 45
	s_mul_hi_u32 s3, s28, 0x600000
	s_add_u32 s2, s8, s2
	v_readlane_b32 s5, v232, 46
	s_addc_u32 s3, s9, s3
	v_mov_b32_e32 v16, v186
	v_readlane_b32 s100, v231, 40
	s_cmpk_eq_u32 s48, 0xf0
	s_cselect_b32 s101, 0x30, 0
	s_add_i32 s100, s100, s101
	s_sub_i32 s101, s100, s48
	s_cmp_ge_u32 s100, s48
	s_cselect_b32 s100, s101, s100
	s_cmpk_lt_u32 s100, 0x20
	s_cselect_b64 s[4:5], -1, 0
	s_mov_b32 s101, 0
	s_and_b64 vcc, exec, s[4:5]
	s_cbranch_vccz .LBB0_656
	v_ashrrev_i32_e32 v0, 1, v16
	v_and_b32_e32 v13, 0xffffffe0, v0
	v_lshlrev_b32_e32 v0, 4, v16
	v_and_b32_e32 v0, 0x1f0, v0
	v_and_b32_e32 v12, 63, v16
	v_and_b32_e32 v18, 0xffffffc0, v16
	v_add_u32_e32 v21, 0, v0
	v_lshl_add_u64 v[10:11], s[36:37], 0, v[0:1]
	v_ashrrev_i32_e32 v0, 5, v16
	v_add_u32_e32 v14, 0x200, v16
	v_add_u32_e32 v15, 0x400, v16
	v_add_u32_e32 v16, 0x600, v16
	s_movk_i32 s6, 0x204
	s_mov_b64 s[4:5], 0xc00000
	v_ashrrev_i32_e32 v14, 5, v14
	v_ashrrev_i32_e32 v15, 5, v15
	v_ashrrev_i32_e32 v16, 5, v16
	v_mad_u32_u24 v17, v12, s6, 0
	v_lshl_add_u64 v[10:11], v[10:11], 0, s[4:5]
	v_mul_lo_u32 v19, v0, s6
	v_mul_lo_u32 v20, v14, s6
	v_mul_lo_u32 v22, v15, s6
	v_mul_lo_u32 v23, v16, s6
	s_mov_b32 s4, s100
	s_lshl_b32 s8, s4, 6
	s_lshl_b32 s9, s48, 6
	v_add_u32_e32 v17, v17, v18
	v_add_u32_e32 v18, v21, v19
	v_add_u32_e32 v19, v21, v20
	v_add_u32_e32 v20, v21, v22
	v_add_u32_e32 v21, v21, v23
	s_mov_b32 s29, s4
	v_readlane_b32 s5, v231, 41

; __device__ __forceinline__ void convert_job(unsigned char* smem, const float* src, int ld, int col0, int mapkind, int N, int K, const float* scale, bf16_t* dst, int vb, int vG) {
;     ...
;     for (int t = vb; t < ntile; t += vG) {
;         const int n0 = (t % tn) * 64, k0 = (t / tn) * 256;
;         const int np = n0 + lane; int sc;
;         if (mapkind == 0) sc = col0 + np;
; __device__ __forceinline__ void convert_layer(unsigned char* smem, const Params& P, int layer, int skip) {
;     ...
;     for (int r = 0; r < 3; ++r) convert_job(smem, P.w_branch + ((size_t)layer * 3 + r) * 512 * 1024, 1024, 0, 0, 1024, 512, nullptr, wb + W_BR + (size_t)r * 1024 * 512, vb, vG);
.LBB0_656:
	v_readlane_b32 s4, v232, 45
	v_readlane_b32 s5, v232, 46
	v_mov_b32_e32 v16, v186
	v_readlane_b32 s100, v231, 40
	s_cmpk_eq_u32 s48, 0xf0
	s_cselect_b32 s101, 0x10, 0
	s_add_i32 s100, s100, s101
	s_sub_i32 s101, s100, s48
	s_cmp_ge_u32 s100, s48
	s_cselect_b32 s100, s101, s100
	s_cmpk_lt_u32 s100, 0x20
	s_cselect_b64 s[4:5], -1, 0
	s_mov_b32 s101, 0
	s_andn2_b64 vcc, exec, s[4:5]
	v_cndmask_b32_e64 v0, 0, 1, s[4:5]
	v_cmp_ne_u32_e64 s[6:7], 1, v0
	s_cbranch_vccnz .LBB0_659
	v_ashrrev_i32_e32 v0, 1, v16
	v_and_b32_e32 v13, 0xffffffe0, v0
	v_lshlrev_b32_e32 v0, 4, v16
	v_and_b32_e32 v0, 0x1f0, v0
	v_and_b32_e32 v12, 63, v16
	v_and_b32_e32 v18, 0xffffffc0, v16
	v_add_u32_e32 v21, 0, v0
	v_lshl_add_u64 v[10:11], s[36:37], 0, v[0:1]
	v_ashrrev_i32_e32 v0, 5, v16
	v_add_u32_e32 v14, 0x200, v16
	v_add_u32_e32 v15, 0x400, v16
	v_add_u32_e32 v16, 0x600, v16
	s_movk_i32 s29, 0x204
	s_mov_b64 s[4:5], 0xd00000
	v_ashrrev_i32_e32 v14, 5, v14
	v_ashrrev_i32_e32 v15, 5, v15
	v_ashrrev_i32_e32 v16, 5, v16
	s_add_u32 s8, s2, 0x200000
	v_mad_u32_u24 v17, v12, s29, 0
	v_lshl_add_u64 v[10:11], v[10:11], 0, s[4:5]
	v_mul_lo_u32 v19, v0, s29
	v_mul_lo_u32 v20, v14, s29
	v_mul_lo_u32 v22, v15, s29
	v_mul_lo_u32 v23, v16, s29
	s_mov_b32 s4, s100
	s_addc_u32 s9, s3, 0
	s_lshl_b32 s29, s4, 6
	s_lshl_b32 s33, s48, 6
	v_add_u32_e32 v17, v17, v18
	v_add_u32_e32 v18, v21, v19
	v_add_u32_e32 v19, v21, v20
	v_add_u32_e32 v20, v21, v22
	v_add_u32_e32 v21, v21, v23
	s_mov_b32 s50, s4
	v_readlane_b32 s5, v231, 41

; __device__ __forceinline__ void convert_job(unsigned char* smem, const float* src, int ld, int col0, int mapkind, int N, int K, const float* scale, bf16_t* dst, int vb, int vG) {
;     ...
;     for (int t = vb; t < ntile; t += vG) {
;         const int n0 = (t % tn) * 64, k0 = (t / tn) * 256;
;         const int np = n0 + lane; int sc;
;         if (mapkind == 0) sc = col0 + np;
; __device__ __forceinline__ void convert_layer(unsigned char* smem, const Params& P, int layer, int skip) {
;     ...
;     for (int r = 0; r < 3; ++r) convert_job(smem, P.w_branch + ((size_t)layer * 3 + r) * 512 * 1024, 1024, 0, 0, 1024, 512, nullptr, wb + W_BR + (size_t)r * 1024 * 512, vb, vG);
.LBB0_659:
	v_mov_b32_e32 v16, v186
	v_readlane_b32 s100, v231, 40
	s_cmpk_eq_u32 s48, 0xf0
	s_cselect_b32 s101, 0xe0, 0
	s_add_i32 s100, s100, s101
	s_sub_i32 s101, s100, s48
	s_cmp_ge_u32 s100, s48
	s_cselect_b32 s100, s101, s100
	s_cmpk_lt_u32 s100, 0x20
	s_cselect_b64 s[6:7], 0, -1
	s_mov_b32 s101, 0
	s_and_b64 vcc, exec, s[6:7]
	s_cbranch_vccnz .LBB0_662
	v_ashrrev_i32_e32 v0, 1, v16
	v_and_b32_e32 v13, 0xffffffe0, v0
	v_lshlrev_b32_e32 v0, 4, v16
	v_and_b32_e32 v0, 0x1f0, v0
	v_and_b32_e32 v12, 63, v16
	v_and_b32_e32 v18, 0xffffffc0, v16
	v_add_u32_e32 v21, 0, v0
	v_lshl_add_u64 v[10:11], s[36:37], 0, v[0:1]
	v_ashrrev_i32_e32 v0, 5, v16
	v_add_u32_e32 v14, 0x200, v16
	v_add_u32_e32 v15, 0x400, v16
	v_add_u32_e32 v16, 0x600, v16
	s_movk_i32 s6, 0x204
	s_mov_b64 s[4:5], 0xe00000
	v_ashrrev_i32_e32 v14, 5, v14
	v_ashrrev_i32_e32 v15, 5, v15
	v_ashrrev_i32_e32 v16, 5, v16
	s_add_u32 s2, s2, 0x400000
	v_mad_u32_u24 v17, v12, s6, 0
	v_lshl_add_u64 v[10:11], v[10:11], 0, s[4:5]
	v_mul_lo_u32 v19, v0, s6
	v_mul_lo_u32 v20, v14, s6
	v_mul_lo_u32 v22, v15, s6
	v_mul_lo_u32 v23, v16, s6
	s_mov_b32 s4, s100
	s_addc_u32 s3, s3, 0
	s_lshl_b32 s8, s4, 6
	s_lshl_b32 s9, s48, 6
	v_add_u32_e32 v17, v17, v18
	v_add_u32_e32 v18, v21, v19
	v_add_u32_e32 v19, v21, v20
	v_add_u32_e32 v20, v21, v22
	v_add_u32_e32 v21, v21, v23
	s_mov_b32 s29, s4
	v_readlane_b32 s5, v231, 41

; __device__ __forceinline__ void convert_job(unsigned char* smem, const float* src, int ld, int col0, int mapkind, int N, int K, const float* scale, bf16_t* dst, int vb, int vG) {
;     ...
;     for (int t = vb; t < ntile; t += vG) {
;         const int n0 = (t % tn) * 64, k0 = (t / tn) * 256;
;         const int np = n0 + lane; int sc;
;         if (mapkind == 0) sc = col0 + np;
; __device__ __forceinline__ void convert_layer(unsigned char* smem, const Params& P, int layer, int skip) {
;     ...
;     convert_job(smem, P.w_out + (size_t)layer * DM * DM, DM, 0, 0, DM, DM, nullptr, wb + W_OUT, vb, vG);
.LBB0_662:
	v_readlane_b32 s2, v232, 47
	v_readlane_b32 s3, v232, 48
	v_mov_b32_e32 v16, v186
	v_readlane_b32 s100, v231, 40
	s_cmpk_eq_u32 s48, 0xf0
	s_cselect_b32 s101, 0xc0, 0
	s_add_i32 s100, s100, s101
	s_sub_i32 s101, s100, s48
	s_cmp_ge_u32 s100, s48
	s_cselect_b32 s100, s101, s100
	s_cmpk_lt_u32 s100, 0x40
	s_cselect_b64 s[2:3], -1, 0
	s_mov_b32 s101, 0
	s_and_b64 vcc, exec, s[2:3]
	s_cbranch_vccz .LBB0_665
	v_ashrrev_i32_e32 v0, 1, v16
	v_and_b32_e32 v13, 0xffffffe0, v0
	v_lshlrev_b32_e32 v0, 4, v16
	v_and_b32_e32 v0, 0x1f0, v0
	v_and_b32_e32 v12, 63, v16
	v_and_b32_e32 v18, 0xffffffc0, v16
	v_add_u32_e32 v21, 0, v0
	v_lshl_add_u64 v[10:11], s[36:37], 0, v[0:1]
	v_ashrrev_i32_e32 v0, 5, v16
	v_add_u32_e32 v14, 0x200, v16
	v_add_u32_e32 v15, 0x400, v16
	v_add_u32_e32 v16, 0x600, v16
	s_lshl_b64 s[2:3], s[40:41], 2
	s_movk_i32 s6, 0x204
	s_mov_b64 s[4:5], 0xf00000
	v_ashrrev_i32_e32 v14, 5, v14
	v_ashrrev_i32_e32 v15, 5, v15
	v_ashrrev_i32_e32 v16, 5, v16
	s_add_u32 s2, s10, s2
	v_mad_u32_u24 v17, v12, s6, 0
	v_lshl_add_u64 v[10:11], v[10:11], 0, s[4:5]
	v_mul_lo_u32 v19, v0, s6
	v_mul_lo_u32 v20, v14, s6
	v_mul_lo_u32 v22, v15, s6
	v_mul_lo_u32 v23, v16, s6
	s_mov_b32 s4, s100
	s_addc_u32 s3, s11, s3
	s_lshl_b32 s8, s4, 6
	s_lshl_b32 s9, s48, 6
	v_add_u32_e32 v17, v17, v18
	v_add_u32_e32 v18, v21, v19
	v_add_u32_e32 v19, v21, v20
	v_add_u32_e32 v20, v21, v22
	v_add_u32_e32 v21, v21, v23
	s_mov_b32 s10, s4
	v_readlane_b32 s5, v231, 41

; __device__ __forceinline__ void convert_job(unsigned char* smem, const float* src, int ld, int col0, int mapkind, int N, int K, const float* scale, bf16_t* dst, int vb, int vG) {
;     ...
;     for (int t = vb; t < ntile; t += vG) {
;         const int n0 = (t % tn) * 64, k0 = (t / tn) * 256;
;         const int np = n0 + lane; int sc;
;         if (mapkind == 0) sc = col0 + np;
; __device__ __forceinline__ void convert_layer(unsigned char* smem, const Params& P, int layer, int skip) {
;     ...
;     convert_job(smem, P.w_ffn_in + (size_t)layer * DM * 2 * FFH, 2 * FFH, 0, 1, 2 * FFH, DM, P.norm_ffn + layer * DM, wb + W_FFI, vb, vG);
.LBB0_665:
	v_readlane_b32 s2, v232, 49
	v_readlane_b32 s3, v232, 50
	v_mov_b32_e32 v12, v186
	v_readlane_b32 s100, v231, 40
	s_cmpk_eq_u32 s48, 0xf0
	s_cselect_b32 s101, 0x80, 0
	s_add_i32 s100, s100, s101
	s_sub_i32 s101, s100, s48
	s_cmp_ge_u32 s100, s48
	s_cselect_b32 s100, s101, s100
	s_mov_b32 s101, 0
	s_andn2_b64 vcc, exec, s[2:3]
	s_cbranch_vccnz .LBB0_670
	s_mul_i32 s2, s28, 0x1600000
	v_ashrrev_i32_e32 v0, 1, v12
	s_mul_hi_u32 s3, s28, 0x1600000
	s_add_u32 s2, s14, s2
	v_and_b32_e32 v47, 0xffffffe0, v0
	v_lshlrev_b32_e32 v0, 4, v12
	s_addc_u32 s3, s15, s3
	v_and_b32_e32 v0, 0x1f0, v0
	s_add_u32 s6, s12, s38
	v_and_b32_e32 v46, 63, v12
	v_and_b32_e32 v14, 0xffffffc0, v12
	v_add_u32_e32 v15, 0, v0
	v_lshl_add_u64 v[10:11], s[36:37], 0, v[0:1]
	v_ashrrev_i32_e32 v0, 5, v12
	v_add_u32_e32 v17, 0x200, v12
	v_add_u32_e32 v18, 0x400, v12
	v_add_u32_e32 v12, 0x600, v12
	s_addc_u32 s7, s13, s39
	s_movk_i32 s10, 0x204
	s_mov_b64 s[4:5], 0x1100000
	v_ashrrev_i32_e32 v48, 5, v17
	v_ashrrev_i32_e32 v49, 5, v18
	v_ashrrev_i32_e32 v50, 5, v12
	s_cmp_lg_u64 s[12:13], 0
	v_mad_u32_u24 v13, v46, s10, 0
	v_lshl_add_u64 v[10:11], v[10:11], 0, s[4:5]
	v_mul_lo_u32 v16, v0, s10
	v_mul_lo_u32 v17, v48, s10
	v_mul_lo_u32 v18, v49, s10
	v_mul_lo_u32 v12, v50, s10
	s_mov_b32 s4, s100
	s_cselect_b64 s[8:9], -1, 0
	s_lshl_b32 s12, s4, 6
	s_lshl_b32 s13, s48, 6
	s_lshl_b32 s14, s4, 5
	s_lshl_b32 s15, s48, 5
	v_add_u32_e32 v51, v13, v14
	v_add_u32_e32 v52, v15, v16
	v_add_u32_e32 v53, v15, v17
	v_add_u32_e32 v54, v15, v18
	v_add_u32_e32 v55, v15, v12
	s_mov_b32 s29, s4
	v_readlane_b32 s5, v231, 41
	s_branch .LBB0_668

; __device__ __forceinline__ void convert_job(unsigned char* smem, const float* src, int ld, int col0, int mapkind, int N, int K, const float* scale, bf16_t* dst, int vb, int vG) {
;     ...
;     for (int t = vb; t < ntile; t += vG) {
;         const int n0 = (t % tn) * 64, k0 = (t / tn) * 256;
;         const int np = n0 + lane; int sc;
;         if (mapkind == 0) sc = col0 + np;
; __device__ __forceinline__ void convert_layer(unsigned char* smem, const Params& P, int layer, int skip) {
;     ...
;     convert_job(smem, P.w_ffn_out + (size_t)layer * FFH * DM, DM, 0, 0, DM, FFH, nullptr, wb + W_FFO, vb, vG);
.LBB0_670:
	v_mov_b32_e32 v16, v186
	v_readlane_b32 s100, v231, 40
	s_cmpk_eq_u32 s48, 0xf0
	s_cselect_b32 s101, 0x10, 0
	s_add_i32 s100, s100, s101
	s_sub_i32 s101, s100, s48
	s_cmp_ge_u32 s100, s48
	s_cselect_b32 s100, s101, s100
	s_cmpk_lt_u32 s100, 0xb0
	s_cselect_b64 s[26:27], 0, -1
	s_mov_b32 s101, 0
	s_and_b64 vcc, exec, s[26:27]
	s_cbranch_vccnz .LBB0_673
	v_ashrrev_i32_e32 v0, 1, v16
	v_and_b32_e32 v13, 0xffffffe0, v0
	v_lshlrev_b32_e32 v0, 4, v16
	v_and_b32_e32 v0, 0x1f0, v0
	v_and_b32_e32 v12, 63, v16
	v_and_b32_e32 v18, 0xffffffc0, v16
	v_add_u32_e32 v21, 0, v0
	v_lshl_add_u64 v[10:11], s[36:37], 0, v[0:1]
	v_ashrrev_i32_e32 v0, 5, v16
	v_add_u32_e32 v14, 0x200, v16
	v_add_u32_e32 v15, 0x400, v16
	v_add_u32_e32 v16, 0x600, v16
	s_mul_i32 s2, s28, 0xb00000
	s_movk_i32 s6, 0x204
	s_mov_b64 s[4:5], 0x1c00000
	v_ashrrev_i32_e32 v14, 5, v14
	v_ashrrev_i32_e32 v15, 5, v15
	v_ashrrev_i32_e32 v16, 5, v16
	s_mul_hi_u32 s3, s28, 0xb00000
	s_add_u32 s2, s16, s2
	v_mad_u32_u24 v17, v12, s6, 0
	v_lshl_add_u64 v[10:11], v[10:11], 0, s[4:5]
	v_mul_lo_u32 v19, v0, s6
	v_mul_lo_u32 v20, v14, s6
	v_mul_lo_u32 v22, v15, s6
	v_mul_lo_u32 v23, v16, s6
	s_mov_b32 s4, s100
	s_addc_u32 s3, s17, s3
	s_lshl_b32 s8, s4, 6
	s_lshl_b32 s9, s48, 6
	v_add_u32_e32 v17, v17, v18
	v_add_u32_e32 v18, v21, v19
	v_add_u32_e32 v19, v21, v20
	v_add_u32_e32 v20, v21, v22
	v_add_u32_e32 v21, v21, v23
	s_mov_b32 s10, s4
	v_readlane_b32 s5, v231, 41

; __device__ __forceinline__ void convert_job(unsigned char* smem, const float* src, int ld, int col0, int mapkind, int N, int K, const float* scale, bf16_t* dst, int vb, int vG) {
;     ...
;     for (int t = vb; t < ntile; t += vG) {
;         const int n0 = (t % tn) * 64, k0 = (t / tn) * 256;
;         const int np = n0 + lane; int sc;
;         if (mapkind == 0) sc = col0 + np;
; __device__ __forceinline__ void convert_layer(unsigned char* smem, const Params& P, int layer, int skip) {
;     ...
;     convert_job(smem, P.w_ple_gate + (size_t)layer * DM * DM, DM, 0, 0, DM, DM, P.norm_ple + layer * DM, wb + W_PG, vb, vG);
.LBB0_673:
	v_readlane_b32 s2, v232, 47
	v_readlane_b32 s3, v232, 48
	v_mov_b32_e32 v12, v186
	v_readlane_b32 s100, v231, 40
	s_cmpk_eq_u32 s48, 0xf0
	s_cselect_b32 s101, 0x50, 0
	s_add_i32 s100, s100, s101
	s_sub_i32 s101, s100, s48
	s_cmp_ge_u32 s100, s48
	s_cselect_b32 s100, s101, s100
	s_cmpk_lt_u32 s100, 0x40
	s_cselect_b64 s[2:3], -1, 0
	s_mov_b32 s101, 0
	s_andn2_b64 vcc, exec, s[2:3]
	s_cbranch_vccnz .LBB0_678
	s_lshl_b64 s[2:3], s[40:41], 2
	v_ashrrev_i32_e32 v0, 1, v12
	s_add_u32 s2, s20, s2
	v_and_b32_e32 v49, 0xffffffe0, v0
	v_lshlrev_b32_e32 v0, 4, v12
	s_addc_u32 s3, s21, s3
	v_and_b32_e32 v0, 0x1f0, v0
	s_add_u32 s6, s18, s38
	v_and_b32_e32 v48, 63, v12
	v_and_b32_e32 v14, 0xffffffc0, v12
	v_add_u32_e32 v15, 0, v0
	v_lshl_add_u64 v[10:11], s[36:37], 0, v[0:1]
	v_ashrrev_i32_e32 v0, 5, v12
	v_add_u32_e32 v17, 0x200, v12
	v_add_u32_e32 v18, 0x400, v12
	v_add_u32_e32 v12, 0x600, v12
	s_addc_u32 s7, s19, s39
	s_movk_i32 s10, 0x204
	s_mov_b64 s[4:5], 0x2180000
	v_ashrrev_i32_e32 v50, 5, v17
	v_ashrrev_i32_e32 v51, 5, v18
	v_ashrrev_i32_e32 v52, 5, v12
	s_cmp_lg_u64 s[18:19], 0
	v_mad_u32_u24 v13, v48, s10, 0
	v_lshl_add_u64 v[10:11], v[10:11], 0, s[4:5]
	v_mul_lo_u32 v16, v0, s10
	v_mul_lo_u32 v17, v50, s10
	v_mul_lo_u32 v18, v51, s10
	v_mul_lo_u32 v12, v52, s10
	s_mov_b32 s4, s100
	s_cselect_b64 s[8:9], -1, 0
	s_lshl_b32 s12, s4, 6
	s_lshl_b32 s13, s48, 6
	v_add_u32_e32 v53, v13, v14
	v_add_u32_e32 v54, v15, v16
	v_add_u32_e32 v55, v15, v17
	v_add_u32_e32 v56, v15, v18
	v_add_u32_e32 v57, v15, v12
	s_mov_b32 s14, s4
	v_readlane_b32 s5, v231, 41
	s_branch .LBB0_676

; __device__ __forceinline__ void convert_job(unsigned char* smem, const float* src, int ld, int col0, int mapkind, int N, int K, const float* scale, bf16_t* dst, int vb, int vG) {
;     ...
;     for (int t = vb; t < ntile; t += vG) {
;         const int n0 = (t % tn) * 64, k0 = (t / tn) * 256;
;         const int np = n0 + lane; int sc;
;         if (mapkind == 0) sc = col0 + np;
; __device__ __forceinline__ void convert_layer(unsigned char* smem, const Params& P, int layer, int skip) {
;     ...
;     convert_job(smem, P.w_ple_proj + (size_t)layer * 256 * DM, DM, 0, 0, DM, 256, nullptr, wb + W_PP, vb, vG);
.LBB0_678:
	v_mov_b32_e32 v16, v186
	v_readlane_b32 s100, v231, 40
	s_cmpk_eq_u32 s48, 0xf0
	s_cselect_b32 s101, 0x10, 0
	s_add_i32 s100, s100, s101
	s_sub_i32 s101, s100, s48
	s_cmp_ge_u32 s100, s48
	s_cselect_b32 s100, s101, s100
	s_cmpk_lt_u32 s100, 0x10
	s_cselect_b64 s[24:25], 0, -1
	s_mov_b32 s101, 0
	s_and_b64 vcc, exec, s[24:25]
	s_cbranch_vccnz .LBB0_681
	v_ashrrev_i32_e32 v0, 1, v16
	v_and_b32_e32 v13, 0xffffffe0, v0
	v_lshlrev_b32_e32 v0, 4, v16
	v_and_b32_e32 v0, 0x1f0, v0
	v_and_b32_e32 v12, 63, v16
	v_and_b32_e32 v18, 0xffffffc0, v16
	v_add_u32_e32 v21, 0, v0
	v_lshl_add_u64 v[10:11], s[36:37], 0, v[0:1]
	v_ashrrev_i32_e32 v0, 5, v16
	v_add_u32_e32 v14, 0x200, v16
	v_add_u32_e32 v15, 0x400, v16
	v_add_u32_e32 v16, 0x600, v16
	s_movk_i32 s6, 0x204
	s_mov_b64 s[4:5], 0x2380000
	v_ashrrev_i32_e32 v14, 5, v14
	v_ashrrev_i32_e32 v15, 5, v15
	v_ashrrev_i32_e32 v16, 5, v16
	s_add_u32 s2, s22, s40
	v_mad_u32_u24 v17, v12, s6, 0
	v_lshl_add_u64 v[10:11], v[10:11], 0, s[4:5]
	v_mul_lo_u32 v19, v0, s6
	v_mul_lo_u32 v20, v14, s6
	v_mul_lo_u32 v22, v15, s6
	v_mul_lo_u32 v23, v16, s6
	s_mov_b32 s4, s100
	s_addc_u32 s3, s23, s41
	s_lshl_b32 s8, s4, 6
	s_lshl_b32 s9, s48, 6
	v_add_u32_e32 v17, v17, v18
	v_add_u32_e32 v18, v21, v19
	v_add_u32_e32 v19, v21, v20
	v_add_u32_e32 v20, v21, v22
	v_add_u32_e32 v21, v21, v23
	s_mov_b32 s10, s4
	v_readlane_b32 s5, v231, 41
